# prologue/epilogue de-serialisation: NSA item epilogue issues its 16 gate loads together (one base + immediate offsets) and waits once, instead of 16 load->vmcnt(0)->store round trips
# baseline (speedup 1.0000x reference)
; DI unsigned pk2(float lo, float hi) { f32x2 v = {lo, hi}; bf16x2_t b = __builtin_convertvector(v, bf16x2_t); return __builtin_bit_cast(unsigned, b); }
; DI float lo16(unsigned u) { return __uint_as_float(u << 16); }
; DI float hi16(unsigned u) { return __uint_as_float(u & 0xffff0000u); }
; DI float siluf_(float x) { return x * __builtin_amdgcn_rcpf(1.f + __expf(-x)); }
; DI int opaque_i(int v) { asm volatile("" : "+v"(v)); return v; }
; DI void nsa_block_item(const Params& P, unsigned char* smem_g, int b, int g, int tb, int tid_in) {
;     ...
;     {
;         const int lane2 = opaque_i(lane); const int hh = lane2 >> 5, head = g * 8 + (lane2 & 7); const unsigned tok = (unsigned)(b * TT + t0 + ((lane2 & 31) >> 3));
;         const unsigned poff = tok * (unsigned)LDP, ooff = tok * 4096u + 2048u + (unsigned)head * 128u;
;         const float inv = st.l > 0.f ? g1 / st.l : 0.f;
; #pragma unroll
;         for (int dt = 0; dt < 4; ++dt)
; #pragma unroll
;             for (int ig = 0; ig < 4; ++ig) { const int d0 = 32 * dt + 8 * ig + 4 * hh;
;                 const u32x2 zz = *(const u32x2*)(P_proj + (poff + C_ZNSA + head * 128 + d0)); const u32x2 pv = totw[(dt * 4 + ig) * 64 + lane];
;                 const float o0 = st.acc[dt][4 * ig + 0] * inv + lo16(pv.x), o1 = st.acc[dt][4 * ig + 1] * inv + hi16(pv.x), o2 = st.acc[dt][4 * ig + 2] * inv + lo16(pv.y), o3 = st.acc[dt][4 * ig + 3] * inv + hi16(pv.y);
;                 u32x2 w; w.x = pk2(o0 * siluf_(lo16(zz.x)), o1 * siluf_(hi16(zz.x))); w.y = pk2(o2 * siluf_(lo16(zz.y)), o3 * siluf_(hi16(zz.y)));
;                 *(u32x2*)(P_onsa + (ooff + d0)) = w; }
.LBB0_379:
	s_add_i32 s59, s59, s60
	v_lshrrev_b32_e32 v2, 3, v155
	v_and_or_b32 v0, v155, 7, s58
	v_and_or_b32 v6, v2, 3, s59
	v_mul_lo_u32 v2, v6, s44
	v_lshlrev_b32_e32 v9, 7, v0
	v_ashrrev_i32_e32 v0, 3, v155
	v_and_b32_e32 v8, -4, v0
	v_add3_u32 v7, v9, v2, s55
	v_add_u32_e32 v0, v7, v8
	v_lshl_add_u64 v[2:3], v[0:1], 1, s[30:31]
	global_load_dwordx2 v[14:15], v[2:3], off
	global_load_dwordx2 v[98:99], v[2:3], off offset:16
	global_load_dwordx2 v[100:101], v[2:3], off offset:32
	global_load_dwordx2 v[102:103], v[2:3], off offset:48
	global_load_dwordx2 v[104:105], v[2:3], off offset:64
	global_load_dwordx2 v[106:107], v[2:3], off offset:80
	global_load_dwordx2 v[108:109], v[2:3], off offset:96
	global_load_dwordx2 v[110:111], v[2:3], off offset:112
	global_load_dwordx2 v[112:113], v[2:3], off offset:128
	global_load_dwordx2 v[114:115], v[2:3], off offset:144
	global_load_dwordx2 v[116:117], v[2:3], off offset:160
	global_load_dwordx2 v[118:119], v[2:3], off offset:176
	global_load_dwordx2 v[120:121], v[2:3], off offset:192
	global_load_dwordx2 v[122:123], v[2:3], off offset:208
	global_load_dwordx2 v[124:125], v[2:3], off offset:224
	global_load_dwordx2 v[126:127], v[2:3], off offset:240
	v_and_b32_e32 v0, 0xffff0000, v154
	v_mul_f32_e32 v0, 0xbfb8aa3b, v0
	v_exp_f32_e32 v0, v0
	v_lshlrev_b32_e32 v6, 12, v6
	v_or3_b32 v9, v6, v9, s56
	v_add_u32_e32 v28, 8, v8
	v_add_f32_e32 v6, 1.0, v0
	v_rcp_f32_e32 v6, v6
	v_add_u32_e32 v0, v9, v8
	v_lshl_add_u64 v[18:19], v[0:1], 1, s[28:29]
	v_add_u32_e32 v0, v7, v28
	v_div_scale_f32 v22, s[0:1], v163, v163, v6
	v_rcp_f32_e32 v23, v22
	v_lshl_add_u64 v[20:21], v[0:1], 1, s[30:31]
	v_div_scale_f32 v0, vcc, v6, v163, v6
	v_fma_f32 v24, -v22, v23, 1.0
	v_fmac_f32_e32 v23, v24, v23
	v_mul_f32_e32 v24, v0, v23
	v_fma_f32 v25, -v22, v24, v0
	v_fmac_f32_e32 v24, v25, v23
	v_fma_f32 v0, -v22, v24, v0
	v_div_fmas_f32 v0, v0, v23, v24
	v_div_fixup_f32 v0, v0, v163, v6
	v_cmp_lt_f32_e32 vcc, 0, v163
	ds_read2st64_b64 v[10:13], v157 offset1:1
	ds_read2st64_b64 v[2:5], v157 offset0:2 offset1:3
	v_cndmask_b32_e32 v6, 0, v0, vcc
	s_add_i32 s57, s57, s10
	s_cmpk_lt_i32 s57, 0x800
	s_waitcnt lgkmcnt(0)
	v_lshlrev_b32_e32 v16, 16, v10
	v_and_b32_e32 v17, 0xffff0000, v10
	v_lshlrev_b32_e32 v10, 16, v11
	v_and_b32_e32 v11, 0xffff0000, v11
	v_pk_fma_f32 v[16:17], v[80:81], v[6:7], v[16:17] op_sel_hi:[1,0,1]
	v_pk_fma_f32 v[10:11], v[82:83], v[6:7], v[10:11] op_sel_hi:[1,0,1]
	s_waitcnt vmcnt(0)
	v_lshlrev_b32_e32 v22, 16, v14
	v_and_b32_e32 v23, 0xffff0000, v14
	v_lshlrev_b32_e32 v14, 16, v15
	v_and_b32_e32 v15, 0xffff0000, v15
	v_mul_f32_e32 v0, 0xbfb8aa3b, v22
	v_mul_f32_e32 v24, 0xbfb8aa3b, v23
	v_mul_f32_e32 v25, 0xbfb8aa3b, v14
	v_mul_f32_e32 v26, 0xbfb8aa3b, v15
	v_exp_f32_e32 v0, v0
	v_exp_f32_e32 v24, v24
	v_exp_f32_e32 v25, v25
	v_exp_f32_e32 v26, v26
	v_add_f32_e32 v0, 1.0, v0
	v_add_f32_e32 v27, 1.0, v24
	v_add_f32_e32 v29, 1.0, v25
	v_add_f32_e32 v30, 1.0, v26
	v_rcp_f32_e32 v24, v0
	v_rcp_f32_e32 v25, v27
	v_rcp_f32_e32 v26, v29
	v_rcp_f32_e32 v27, v30
	v_add_u32_e32 v0, v9, v28
	v_pk_mul_f32 v[22:23], v[24:25], v[22:23]
	v_pk_mul_f32 v[14:15], v[26:27], v[14:15]
	v_pk_mul_f32 v[16:17], v[16:17], v[22:23]
	v_pk_mul_f32 v[10:11], v[10:11], v[14:15]
	v_cvt_pk_bf16_f32 v14, v16, v17
	v_cvt_pk_bf16_f32 v15, v10, v11
	global_store_dwordx2 v[18:19], v[14:15], off
	v_mov_b64_e32 v[10:11], v[98:99]
	v_add_u32_e32 v26, 16, v8
	v_lshl_add_u64 v[16:17], v[0:1], 1, s[28:29]
	v_add_u32_e32 v0, v7, v26
	v_lshl_add_u64 v[18:19], v[0:1], 1, s[30:31]
	v_lshlrev_b32_e32 v14, 16, v12
	v_and_b32_e32 v15, 0xffff0000, v12
	v_lshlrev_b32_e32 v12, 16, v13
	v_and_b32_e32 v13, 0xffff0000, v13
	v_pk_fma_f32 v[14:15], v[84:85], v[6:7], v[14:15] op_sel_hi:[1,0,1]
	v_pk_fma_f32 v[12:13], v[86:87], v[6:7], v[12:13] op_sel_hi:[1,0,1]
	v_lshlrev_b32_e32 v20, 16, v10
	v_and_b32_e32 v21, 0xffff0000, v10
	v_lshlrev_b32_e32 v10, 16, v11
	v_and_b32_e32 v11, 0xffff0000, v11
	v_mul_f32_e32 v0, 0xbfb8aa3b, v20
	v_mul_f32_e32 v22, 0xbfb8aa3b, v21
	v_mul_f32_e32 v23, 0xbfb8aa3b, v10
	v_mul_f32_e32 v24, 0xbfb8aa3b, v11
	v_exp_f32_e32 v0, v0
	v_exp_f32_e32 v22, v22
	v_exp_f32_e32 v23, v23
	v_exp_f32_e32 v24, v24
	v_add_f32_e32 v0, 1.0, v0
	v_add_f32_e32 v25, 1.0, v22
	v_add_f32_e32 v27, 1.0, v23
	v_add_f32_e32 v28, 1.0, v24
	v_rcp_f32_e32 v22, v0
	v_rcp_f32_e32 v23, v25
	v_rcp_f32_e32 v24, v27
	v_rcp_f32_e32 v25, v28
	v_add_u32_e32 v0, v9, v26
	v_pk_mul_f32 v[20:21], v[22:23], v[20:21]
	v_add_u32_e32 v28, 40, v8
	v_pk_mul_f32 v[10:11], v[24:25], v[10:11]
	v_pk_mul_f32 v[14:15], v[14:15], v[20:21]
	v_pk_mul_f32 v[10:11], v[12:13], v[10:11]
	v_cvt_pk_bf16_f32 v12, v14, v15
	v_cvt_pk_bf16_f32 v13, v10, v11
	global_store_dwordx2 v[16:17], v[12:13], off
	v_mov_b64_e32 v[10:11], v[100:101]
	v_add_u32_e32 v24, 24, v8
	v_lshl_add_u64 v[14:15], v[0:1], 1, s[28:29]
	v_add_u32_e32 v0, v7, v24
	v_lshl_add_u64 v[16:17], v[0:1], 1, s[30:31]
	v_lshlrev_b32_e32 v12, 16, v2
	v_and_b32_e32 v13, 0xffff0000, v2
	v_lshlrev_b32_e32 v2, 16, v3
	v_and_b32_e32 v3, 0xffff0000, v3
	v_pk_fma_f32 v[12:13], v[88:89], v[6:7], v[12:13] op_sel_hi:[1,0,1]
	v_pk_fma_f32 v[2:3], v[90:91], v[6:7], v[2:3] op_sel_hi:[1,0,1]
	v_lshlrev_b32_e32 v18, 16, v10
	v_and_b32_e32 v19, 0xffff0000, v10
	v_lshlrev_b32_e32 v10, 16, v11
	v_and_b32_e32 v11, 0xffff0000, v11
	v_mul_f32_e32 v0, 0xbfb8aa3b, v18
	v_mul_f32_e32 v20, 0xbfb8aa3b, v19
	v_mul_f32_e32 v21, 0xbfb8aa3b, v10
	v_mul_f32_e32 v22, 0xbfb8aa3b, v11
	v_exp_f32_e32 v0, v0
	v_exp_f32_e32 v20, v20
	v_exp_f32_e32 v21, v21
	v_exp_f32_e32 v22, v22
	v_add_f32_e32 v0, 1.0, v0
	v_add_f32_e32 v23, 1.0, v20
	v_add_f32_e32 v25, 1.0, v21
; DI unsigned pk2(float lo, float hi) { f32x2 v = {lo, hi}; bf16x2_t b = __builtin_convertvector(v, bf16x2_t); return __builtin_bit_cast(unsigned, b); }
; DI float lo16(unsigned u) { return __uint_as_float(u << 16); }
; DI float hi16(unsigned u) { return __uint_as_float(u & 0xffff0000u); }
; DI float siluf_(float x) { return x * __builtin_amdgcn_rcpf(1.f + __expf(-x)); }
; DI void nsa_block_item(const Params& P, unsigned char* smem_g, int b, int g, int tb, int tid_in) {
;     ...
;         for (int dt = 0; dt < 4; ++dt)
; #pragma unroll
;             for (int ig = 0; ig < 4; ++ig) { const int d0 = 32 * dt + 8 * ig + 4 * hh;
;                 const u32x2 zz = *(const u32x2*)(P_proj + (poff + C_ZNSA + head * 128 + d0)); const u32x2 pv = totw[(dt * 4 + ig) * 64 + lane];
;                 const float o0 = st.acc[dt][4 * ig + 0] * inv + lo16(pv.x), o1 = st.acc[dt][4 * ig + 1] * inv + hi16(pv.x), o2 = st.acc[dt][4 * ig + 2] * inv + lo16(pv.y), o3 = st.acc[dt][4 * ig + 3] * inv + hi16(pv.y);
;                 u32x2 w; w.x = pk2(o0 * siluf_(lo16(zz.x)), o1 * siluf_(hi16(zz.x))); w.y = pk2(o2 * siluf_(lo16(zz.y)), o3 * siluf_(hi16(zz.y)));
;                 *(u32x2*)(P_onsa + (ooff + d0)) = w; }
	v_add_f32_e32 v26, 1.0, v22
	v_rcp_f32_e32 v20, v0
	v_rcp_f32_e32 v21, v23
	v_rcp_f32_e32 v22, v25
	v_rcp_f32_e32 v23, v26
	v_add_u32_e32 v0, v9, v24
	v_pk_mul_f32 v[18:19], v[20:21], v[18:19]
	v_pk_mul_f32 v[10:11], v[22:23], v[10:11]
	v_pk_mul_f32 v[12:13], v[12:13], v[18:19]
	v_pk_mul_f32 v[2:3], v[2:3], v[10:11]
	v_cvt_pk_bf16_f32 v10, v12, v13
	v_cvt_pk_bf16_f32 v11, v2, v3
	global_store_dwordx2 v[14:15], v[10:11], off
	v_mov_b64_e32 v[2:3], v[102:103]
	v_add_u32_e32 v22, 32, v8
	v_lshl_add_u64 v[12:13], v[0:1], 1, s[28:29]
	v_add_u32_e32 v0, v7, v22
	v_lshl_add_u64 v[14:15], v[0:1], 1, s[30:31]
	v_lshlrev_b32_e32 v10, 16, v4
	v_and_b32_e32 v11, 0xffff0000, v4
	v_lshlrev_b32_e32 v4, 16, v5
	v_and_b32_e32 v5, 0xffff0000, v5
	v_pk_fma_f32 v[10:11], v[92:93], v[6:7], v[10:11] op_sel_hi:[1,0,1]
	v_pk_fma_f32 v[4:5], v[94:95], v[6:7], v[4:5] op_sel_hi:[1,0,1]
	v_lshlrev_b32_e32 v16, 16, v2
	v_and_b32_e32 v17, 0xffff0000, v2
	v_lshlrev_b32_e32 v2, 16, v3
	v_and_b32_e32 v3, 0xffff0000, v3
	v_mul_f32_e32 v0, 0xbfb8aa3b, v16
	v_mul_f32_e32 v18, 0xbfb8aa3b, v17
	v_mul_f32_e32 v19, 0xbfb8aa3b, v2
	v_mul_f32_e32 v20, 0xbfb8aa3b, v3
	v_exp_f32_e32 v0, v0
	v_exp_f32_e32 v18, v18
	v_exp_f32_e32 v19, v19
	v_exp_f32_e32 v20, v20
	v_add_f32_e32 v0, 1.0, v0
	v_add_f32_e32 v21, 1.0, v18
	v_add_f32_e32 v23, 1.0, v19
	v_add_f32_e32 v24, 1.0, v20
	v_rcp_f32_e32 v18, v0
	v_rcp_f32_e32 v19, v21
	v_rcp_f32_e32 v20, v23
	v_rcp_f32_e32 v21, v24
	v_add_u32_e32 v0, v9, v22
	v_pk_mul_f32 v[16:17], v[18:19], v[16:17]
	v_lshl_add_u64 v[18:19], v[0:1], 1, s[28:29]
	v_pk_mul_f32 v[2:3], v[20:21], v[2:3]
	v_pk_mul_f32 v[10:11], v[10:11], v[16:17]
	v_pk_mul_f32 v[2:3], v[4:5], v[2:3]
	v_cvt_pk_bf16_f32 v4, v10, v11
	v_cvt_pk_bf16_f32 v5, v2, v3
	global_store_dwordx2 v[12:13], v[4:5], off
	v_mov_b64_e32 v[14:15], v[104:105]
	v_add_u32_e32 v0, v7, v28
	v_lshl_add_u64 v[20:21], v[0:1], 1, s[30:31]
	ds_read2st64_b64 v[2:5], v157 offset0:4 offset1:5
	ds_read2st64_b64 v[10:13], v157 offset0:6 offset1:7
	s_waitcnt lgkmcnt(1)
	v_lshlrev_b32_e32 v16, 16, v2
	v_and_b32_e32 v17, 0xffff0000, v2
	v_lshlrev_b32_e32 v2, 16, v3
	v_and_b32_e32 v3, 0xffff0000, v3
	v_pk_fma_f32 v[16:17], v[64:65], v[6:7], v[16:17] op_sel_hi:[1,0,1]
	v_pk_fma_f32 v[2:3], v[66:67], v[6:7], v[2:3] op_sel_hi:[1,0,1]
	v_lshlrev_b32_e32 v22, 16, v14
	v_and_b32_e32 v23, 0xffff0000, v14
	v_lshlrev_b32_e32 v14, 16, v15
	v_and_b32_e32 v15, 0xffff0000, v15
	v_mul_f32_e32 v0, 0xbfb8aa3b, v22
	v_mul_f32_e32 v24, 0xbfb8aa3b, v23
	v_mul_f32_e32 v25, 0xbfb8aa3b, v14
	v_mul_f32_e32 v26, 0xbfb8aa3b, v15
	v_exp_f32_e32 v0, v0
	v_exp_f32_e32 v24, v24
	v_exp_f32_e32 v25, v25
	v_exp_f32_e32 v26, v26
	v_add_f32_e32 v0, 1.0, v0
	v_add_f32_e32 v27, 1.0, v24
	v_add_f32_e32 v29, 1.0, v25
	v_add_f32_e32 v30, 1.0, v26
	v_rcp_f32_e32 v24, v0
	v_rcp_f32_e32 v25, v27
	v_rcp_f32_e32 v26, v29
	v_rcp_f32_e32 v27, v30
	v_add_u32_e32 v0, v9, v28
	v_pk_mul_f32 v[22:23], v[24:25], v[22:23]
	v_pk_mul_f32 v[14:15], v[26:27], v[14:15]
	v_pk_mul_f32 v[16:17], v[16:17], v[22:23]
	v_pk_mul_f32 v[2:3], v[2:3], v[14:15]
	v_cvt_pk_bf16_f32 v14, v16, v17
	v_cvt_pk_bf16_f32 v15, v2, v3
	global_store_dwordx2 v[18:19], v[14:15], off
	v_mov_b64_e32 v[2:3], v[106:107]
	v_add_u32_e32 v26, 48, v8
	v_lshl_add_u64 v[16:17], v[0:1], 1, s[28:29]
	v_add_u32_e32 v0, v7, v26
	v_lshl_add_u64 v[18:19], v[0:1], 1, s[30:31]
	v_lshlrev_b32_e32 v14, 16, v4
	v_and_b32_e32 v15, 0xffff0000, v4
	v_lshlrev_b32_e32 v4, 16, v5
	v_and_b32_e32 v5, 0xffff0000, v5
	v_pk_fma_f32 v[14:15], v[68:69], v[6:7], v[14:15] op_sel_hi:[1,0,1]
	v_pk_fma_f32 v[4:5], v[70:71], v[6:7], v[4:5] op_sel_hi:[1,0,1]
	v_lshlrev_b32_e32 v20, 16, v2
	v_and_b32_e32 v21, 0xffff0000, v2
	v_lshlrev_b32_e32 v2, 16, v3
	v_and_b32_e32 v3, 0xffff0000, v3
	v_mul_f32_e32 v0, 0xbfb8aa3b, v20
	v_mul_f32_e32 v22, 0xbfb8aa3b, v21
	v_mul_f32_e32 v23, 0xbfb8aa3b, v2
	v_mul_f32_e32 v24, 0xbfb8aa3b, v3
	v_exp_f32_e32 v0, v0
	v_exp_f32_e32 v22, v22
	v_exp_f32_e32 v23, v23
	v_exp_f32_e32 v24, v24
	v_add_f32_e32 v0, 1.0, v0
	v_add_f32_e32 v25, 1.0, v22
	v_add_f32_e32 v27, 1.0, v23
	v_add_f32_e32 v28, 1.0, v24
	v_rcp_f32_e32 v22, v0
	v_rcp_f32_e32 v23, v25
	v_rcp_f32_e32 v24, v27
	v_rcp_f32_e32 v25, v28
	v_add_u32_e32 v0, v9, v26
	v_pk_mul_f32 v[20:21], v[22:23], v[20:21]
	v_add_u32_e32 v28, 0x48, v8
	v_pk_mul_f32 v[2:3], v[24:25], v[2:3]
	v_pk_mul_f32 v[14:15], v[14:15], v[20:21]
	v_pk_mul_f32 v[2:3], v[4:5], v[2:3]
	v_cvt_pk_bf16_f32 v4, v14, v15
	v_cvt_pk_bf16_f32 v5, v2, v3
	global_store_dwordx2 v[16:17], v[4:5], off
	v_mov_b64_e32 v[2:3], v[108:109]
	v_add_u32_e32 v24, 56, v8
	v_lshl_add_u64 v[14:15], v[0:1], 1, s[28:29]
	v_add_u32_e32 v0, v7, v24
	v_lshl_add_u64 v[16:17], v[0:1], 1, s[30:31]
	s_waitcnt lgkmcnt(0)
; DI unsigned pk2(float lo, float hi) { f32x2 v = {lo, hi}; bf16x2_t b = __builtin_convertvector(v, bf16x2_t); return __builtin_bit_cast(unsigned, b); }
; DI float lo16(unsigned u) { return __uint_as_float(u << 16); }
; DI float hi16(unsigned u) { return __uint_as_float(u & 0xffff0000u); }
; DI float siluf_(float x) { return x * __builtin_amdgcn_rcpf(1.f + __expf(-x)); }
; DI void nsa_block_item(const Params& P, unsigned char* smem_g, int b, int g, int tb, int tid_in) {
;     ...
;         for (int dt = 0; dt < 4; ++dt)
; #pragma unroll
;             for (int ig = 0; ig < 4; ++ig) { const int d0 = 32 * dt + 8 * ig + 4 * hh;
;                 const u32x2 zz = *(const u32x2*)(P_proj + (poff + C_ZNSA + head * 128 + d0)); const u32x2 pv = totw[(dt * 4 + ig) * 64 + lane];
;                 const float o0 = st.acc[dt][4 * ig + 0] * inv + lo16(pv.x), o1 = st.acc[dt][4 * ig + 1] * inv + hi16(pv.x), o2 = st.acc[dt][4 * ig + 2] * inv + lo16(pv.y), o3 = st.acc[dt][4 * ig + 3] * inv + hi16(pv.y);
;                 u32x2 w; w.x = pk2(o0 * siluf_(lo16(zz.x)), o1 * siluf_(hi16(zz.x))); w.y = pk2(o2 * siluf_(lo16(zz.y)), o3 * siluf_(hi16(zz.y)));
;                 *(u32x2*)(P_onsa + (ooff + d0)) = w; }
	v_lshlrev_b32_e32 v4, 16, v10
	v_and_b32_e32 v5, 0xffff0000, v10
	v_lshlrev_b32_e32 v10, 16, v11
	v_and_b32_e32 v11, 0xffff0000, v11
	v_pk_fma_f32 v[4:5], v[72:73], v[6:7], v[4:5] op_sel_hi:[1,0,1]
	v_pk_fma_f32 v[10:11], v[74:75], v[6:7], v[10:11] op_sel_hi:[1,0,1]
	v_lshlrev_b32_e32 v18, 16, v2
	v_and_b32_e32 v19, 0xffff0000, v2
	v_lshlrev_b32_e32 v2, 16, v3
	v_and_b32_e32 v3, 0xffff0000, v3
	v_mul_f32_e32 v0, 0xbfb8aa3b, v18
	v_mul_f32_e32 v20, 0xbfb8aa3b, v19
	v_mul_f32_e32 v21, 0xbfb8aa3b, v2
	v_mul_f32_e32 v22, 0xbfb8aa3b, v3
	v_exp_f32_e32 v0, v0
	v_exp_f32_e32 v20, v20
	v_exp_f32_e32 v21, v21
	v_exp_f32_e32 v22, v22
	v_add_f32_e32 v0, 1.0, v0
	v_add_f32_e32 v23, 1.0, v20
	v_add_f32_e32 v25, 1.0, v21
	v_add_f32_e32 v26, 1.0, v22
	v_rcp_f32_e32 v20, v0
	v_rcp_f32_e32 v21, v23
	v_rcp_f32_e32 v22, v25
	v_rcp_f32_e32 v23, v26
	v_add_u32_e32 v0, v9, v24
	v_pk_mul_f32 v[18:19], v[20:21], v[18:19]
	v_pk_mul_f32 v[2:3], v[22:23], v[2:3]
	v_pk_mul_f32 v[4:5], v[4:5], v[18:19]
	v_pk_mul_f32 v[2:3], v[10:11], v[2:3]
	v_cvt_pk_bf16_f32 v4, v4, v5
	v_cvt_pk_bf16_f32 v5, v2, v3
	global_store_dwordx2 v[14:15], v[4:5], off
	v_mov_b64_e32 v[2:3], v[110:111]
	v_add_u32_e32 v22, 64, v8
	v_lshlrev_b32_e32 v4, 16, v12
	v_and_b32_e32 v5, 0xffff0000, v12
	v_lshlrev_b32_e32 v10, 16, v13
	v_and_b32_e32 v11, 0xffff0000, v13
	v_lshl_add_u64 v[12:13], v[0:1], 1, s[28:29]
	v_add_u32_e32 v0, v7, v22
	v_lshl_add_u64 v[14:15], v[0:1], 1, s[30:31]
	v_pk_fma_f32 v[4:5], v[76:77], v[6:7], v[4:5] op_sel_hi:[1,0,1]
	v_pk_fma_f32 v[10:11], v[78:79], v[6:7], v[10:11] op_sel_hi:[1,0,1]
	v_lshlrev_b32_e32 v16, 16, v2
	v_and_b32_e32 v17, 0xffff0000, v2
	v_lshlrev_b32_e32 v2, 16, v3
	v_and_b32_e32 v3, 0xffff0000, v3
	v_mul_f32_e32 v0, 0xbfb8aa3b, v16
	v_mul_f32_e32 v18, 0xbfb8aa3b, v17
	v_mul_f32_e32 v19, 0xbfb8aa3b, v2
	v_mul_f32_e32 v20, 0xbfb8aa3b, v3
	v_exp_f32_e32 v0, v0
	v_exp_f32_e32 v18, v18
	v_exp_f32_e32 v19, v19
	v_exp_f32_e32 v20, v20
	v_add_f32_e32 v0, 1.0, v0
	v_add_f32_e32 v21, 1.0, v18
	v_add_f32_e32 v23, 1.0, v19
	v_add_f32_e32 v24, 1.0, v20
	v_rcp_f32_e32 v18, v0
	v_rcp_f32_e32 v19, v21
	v_rcp_f32_e32 v20, v23
	v_rcp_f32_e32 v21, v24
	v_add_u32_e32 v0, v9, v22
	v_pk_mul_f32 v[16:17], v[18:19], v[16:17]
	v_lshl_add_u64 v[18:19], v[0:1], 1, s[28:29]
	v_pk_mul_f32 v[2:3], v[20:21], v[2:3]
	v_pk_mul_f32 v[4:5], v[4:5], v[16:17]
	v_pk_mul_f32 v[2:3], v[10:11], v[2:3]
	v_cvt_pk_bf16_f32 v4, v4, v5
	v_cvt_pk_bf16_f32 v5, v2, v3
	global_store_dwordx2 v[12:13], v[4:5], off
	v_mov_b64_e32 v[14:15], v[112:113]
	v_add_u32_e32 v0, v7, v28
	v_lshl_add_u64 v[20:21], v[0:1], 1, s[30:31]
	ds_read2st64_b64 v[2:5], v157 offset0:8 offset1:9
	ds_read2st64_b64 v[10:13], v157 offset0:10 offset1:11
	s_waitcnt lgkmcnt(1)
	v_lshlrev_b32_e32 v16, 16, v2
	v_and_b32_e32 v17, 0xffff0000, v2
	v_lshlrev_b32_e32 v2, 16, v3
	v_and_b32_e32 v3, 0xffff0000, v3
	v_pk_fma_f32 v[16:17], v[48:49], v[6:7], v[16:17] op_sel_hi:[1,0,1]
	v_pk_fma_f32 v[2:3], v[50:51], v[6:7], v[2:3] op_sel_hi:[1,0,1]
	v_lshlrev_b32_e32 v22, 16, v14
	v_and_b32_e32 v23, 0xffff0000, v14
	v_lshlrev_b32_e32 v14, 16, v15
	v_and_b32_e32 v15, 0xffff0000, v15
	v_mul_f32_e32 v0, 0xbfb8aa3b, v22
	v_mul_f32_e32 v24, 0xbfb8aa3b, v23
	v_mul_f32_e32 v25, 0xbfb8aa3b, v14
	v_mul_f32_e32 v26, 0xbfb8aa3b, v15
	v_exp_f32_e32 v0, v0
	v_exp_f32_e32 v24, v24
	v_exp_f32_e32 v25, v25
	v_exp_f32_e32 v26, v26
	v_add_f32_e32 v0, 1.0, v0
	v_add_f32_e32 v27, 1.0, v24
	v_add_f32_e32 v29, 1.0, v25
	v_add_f32_e32 v30, 1.0, v26
	v_rcp_f32_e32 v24, v0
	v_rcp_f32_e32 v25, v27
	v_rcp_f32_e32 v26, v29
	v_rcp_f32_e32 v27, v30
	v_add_u32_e32 v0, v9, v28
	v_pk_mul_f32 v[22:23], v[24:25], v[22:23]
	v_add_u32_e32 v28, 0x68, v8
	v_pk_mul_f32 v[14:15], v[26:27], v[14:15]
	v_pk_mul_f32 v[16:17], v[16:17], v[22:23]
	v_pk_mul_f32 v[2:3], v[2:3], v[14:15]
	v_cvt_pk_bf16_f32 v14, v16, v17
	v_cvt_pk_bf16_f32 v15, v2, v3
	global_store_dwordx2 v[18:19], v[14:15], off
	v_mov_b64_e32 v[2:3], v[114:115]
	v_lshl_add_u64 v[16:17], v[0:1], 1, s[28:29]
	v_lshlrev_b32_e32 v14, 16, v4
	v_and_b32_e32 v15, 0xffff0000, v4
	v_lshlrev_b32_e32 v4, 16, v5
	v_and_b32_e32 v5, 0xffff0000, v5
	v_pk_fma_f32 v[14:15], v[52:53], v[6:7], v[14:15] op_sel_hi:[1,0,1]
	v_pk_fma_f32 v[4:5], v[54:55], v[6:7], v[4:5] op_sel_hi:[1,0,1]
	v_add_u32_e32 v26, 0x50, v8
	v_lshlrev_b32_e32 v18, 16, v2
	v_and_b32_e32 v19, 0xffff0000, v2
	v_lshlrev_b32_e32 v2, 16, v3
	v_and_b32_e32 v3, 0xffff0000, v3
	v_mul_f32_e32 v0, 0xbfb8aa3b, v18
	v_mul_f32_e32 v20, 0xbfb8aa3b, v19
	v_mul_f32_e32 v21, 0xbfb8aa3b, v2
	v_mul_f32_e32 v22, 0xbfb8aa3b, v3
	v_exp_f32_e32 v0, v0
	v_exp_f32_e32 v20, v20
	v_exp_f32_e32 v21, v21
	v_exp_f32_e32 v22, v22
	v_add_f32_e32 v0, 1.0, v0
	v_add_f32_e32 v23, 1.0, v20
	v_add_f32_e32 v24, 1.0, v21
	v_add_f32_e32 v25, 1.0, v22
	v_rcp_f32_e32 v20, v0
	v_rcp_f32_e32 v21, v23
	v_rcp_f32_e32 v22, v24
	v_rcp_f32_e32 v23, v25
	v_add_u32_e32 v0, v7, v26
	v_pk_mul_f32 v[18:19], v[20:21], v[18:19]
	v_lshl_add_u64 v[24:25], v[0:1], 1, s[30:31]
	v_pk_mul_f32 v[2:3], v[22:23], v[2:3]
	v_pk_mul_f32 v[14:15], v[14:15], v[18:19]
	v_pk_mul_f32 v[2:3], v[4:5], v[2:3]
	v_cvt_pk_bf16_f32 v4, v14, v15
	v_cvt_pk_bf16_f32 v5, v2, v3
	global_store_dwordx2 v[16:17], v[4:5], off
	v_mov_b64_e32 v[2:3], v[116:117]
	v_add_u32_e32 v0, v9, v26
	v_lshl_add_u64 v[14:15], v[0:1], 1, s[28:29]
	s_waitcnt lgkmcnt(0)
; DI unsigned pk2(float lo, float hi) { f32x2 v = {lo, hi}; bf16x2_t b = __builtin_convertvector(v, bf16x2_t); return __builtin_bit_cast(unsigned, b); }
; DI float lo16(unsigned u) { return __uint_as_float(u << 16); }
; DI float hi16(unsigned u) { return __uint_as_float(u & 0xffff0000u); }
; DI float siluf_(float x) { return x * __builtin_amdgcn_rcpf(1.f + __expf(-x)); }
; DI void nsa_block_item(const Params& P, unsigned char* smem_g, int b, int g, int tb, int tid_in) {
;     ...
;         for (int dt = 0; dt < 4; ++dt)
; #pragma unroll
;             for (int ig = 0; ig < 4; ++ig) { const int d0 = 32 * dt + 8 * ig + 4 * hh;
;                 const u32x2 zz = *(const u32x2*)(P_proj + (poff + C_ZNSA + head * 128 + d0)); const u32x2 pv = totw[(dt * 4 + ig) * 64 + lane];
;                 const float o0 = st.acc[dt][4 * ig + 0] * inv + lo16(pv.x), o1 = st.acc[dt][4 * ig + 1] * inv + hi16(pv.x), o2 = st.acc[dt][4 * ig + 2] * inv + lo16(pv.y), o3 = st.acc[dt][4 * ig + 3] * inv + hi16(pv.y);
;                 u32x2 w; w.x = pk2(o0 * siluf_(lo16(zz.x)), o1 * siluf_(hi16(zz.x))); w.y = pk2(o2 * siluf_(lo16(zz.y)), o3 * siluf_(hi16(zz.y)));
;                 *(u32x2*)(P_onsa + (ooff + d0)) = w; }
	v_lshlrev_b32_e32 v4, 16, v10
	v_and_b32_e32 v5, 0xffff0000, v10
	v_lshlrev_b32_e32 v10, 16, v11
	v_and_b32_e32 v11, 0xffff0000, v11
	v_pk_fma_f32 v[4:5], v[56:57], v[6:7], v[4:5] op_sel_hi:[1,0,1]
	v_pk_fma_f32 v[10:11], v[58:59], v[6:7], v[10:11] op_sel_hi:[1,0,1]
	v_add_u32_e32 v24, 0x58, v8
	v_lshlrev_b32_e32 v16, 16, v2
	v_and_b32_e32 v17, 0xffff0000, v2
	v_lshlrev_b32_e32 v2, 16, v3
	v_and_b32_e32 v3, 0xffff0000, v3
	v_mul_f32_e32 v0, 0xbfb8aa3b, v16
	v_mul_f32_e32 v18, 0xbfb8aa3b, v17
	v_mul_f32_e32 v19, 0xbfb8aa3b, v2
	v_mul_f32_e32 v20, 0xbfb8aa3b, v3
	v_exp_f32_e32 v0, v0
	v_exp_f32_e32 v18, v18
	v_exp_f32_e32 v19, v19
	v_exp_f32_e32 v20, v20
	v_add_f32_e32 v0, 1.0, v0
	v_add_f32_e32 v21, 1.0, v18
	v_add_f32_e32 v22, 1.0, v19
	v_add_f32_e32 v23, 1.0, v20
	v_rcp_f32_e32 v18, v0
	v_rcp_f32_e32 v19, v21
	v_rcp_f32_e32 v20, v22
	v_rcp_f32_e32 v21, v23
	v_add_u32_e32 v0, v7, v24
	v_pk_mul_f32 v[16:17], v[18:19], v[16:17]
	v_lshl_add_u64 v[22:23], v[0:1], 1, s[30:31]
	v_pk_mul_f32 v[2:3], v[20:21], v[2:3]
	v_pk_mul_f32 v[4:5], v[4:5], v[16:17]
	v_pk_mul_f32 v[2:3], v[10:11], v[2:3]
	v_cvt_pk_bf16_f32 v4, v4, v5
	v_cvt_pk_bf16_f32 v5, v2, v3
	global_store_dwordx2 v[14:15], v[4:5], off
	v_mov_b64_e32 v[2:3], v[118:119]
	v_add_u32_e32 v0, v9, v24
	v_lshlrev_b32_e32 v4, 16, v12
	v_and_b32_e32 v5, 0xffff0000, v12
	v_lshlrev_b32_e32 v10, 16, v13
	v_and_b32_e32 v11, 0xffff0000, v13
	v_lshl_add_u64 v[12:13], v[0:1], 1, s[28:29]
	v_pk_fma_f32 v[4:5], v[60:61], v[6:7], v[4:5] op_sel_hi:[1,0,1]
	v_pk_fma_f32 v[10:11], v[62:63], v[6:7], v[10:11] op_sel_hi:[1,0,1]
	v_add_u32_e32 v22, 0x60, v8
	v_lshlrev_b32_e32 v14, 16, v2
	v_and_b32_e32 v15, 0xffff0000, v2
	v_lshlrev_b32_e32 v2, 16, v3
	v_and_b32_e32 v3, 0xffff0000, v3
	v_mul_f32_e32 v0, 0xbfb8aa3b, v14
	v_mul_f32_e32 v16, 0xbfb8aa3b, v15
	v_mul_f32_e32 v17, 0xbfb8aa3b, v2
	v_mul_f32_e32 v18, 0xbfb8aa3b, v3
	v_exp_f32_e32 v0, v0
	v_exp_f32_e32 v16, v16
	v_exp_f32_e32 v17, v17
	v_exp_f32_e32 v18, v18
	v_add_f32_e32 v0, 1.0, v0
	v_add_f32_e32 v19, 1.0, v16
	v_add_f32_e32 v20, 1.0, v17
	v_add_f32_e32 v21, 1.0, v18
	v_rcp_f32_e32 v16, v0
	v_rcp_f32_e32 v17, v19
	v_rcp_f32_e32 v18, v20
	v_rcp_f32_e32 v19, v21
	v_add_u32_e32 v0, v7, v22
	v_pk_mul_f32 v[14:15], v[16:17], v[14:15]
	v_lshl_add_u64 v[20:21], v[0:1], 1, s[30:31]
	v_pk_mul_f32 v[2:3], v[18:19], v[2:3]
	v_pk_mul_f32 v[4:5], v[4:5], v[14:15]
	v_pk_mul_f32 v[2:3], v[10:11], v[2:3]
	v_cvt_pk_bf16_f32 v4, v4, v5
	v_cvt_pk_bf16_f32 v5, v2, v3
	global_store_dwordx2 v[12:13], v[4:5], off
	v_mov_b64_e32 v[14:15], v[120:121]
	v_add_u32_e32 v0, v9, v22
	v_lshl_add_u64 v[18:19], v[0:1], 1, s[28:29]
	ds_read2st64_b64 v[2:5], v157 offset0:12 offset1:13
	ds_read2st64_b64 v[10:13], v157 offset0:14 offset1:15
	s_waitcnt lgkmcnt(1)
; DI unsigned pk2(float lo, float hi) { f32x2 v = {lo, hi}; bf16x2_t b = __builtin_convertvector(v, bf16x2_t); return __builtin_bit_cast(unsigned, b); }
; DI float lo16(unsigned u) { return __uint_as_float(u << 16); }
; DI float hi16(unsigned u) { return __uint_as_float(u & 0xffff0000u); }
; DI float siluf_(float x) { return x * __builtin_amdgcn_rcpf(1.f + __expf(-x)); }
; DI void nsa_block_item(const Params& P, unsigned char* smem_g, int b, int g, int tb, int tid_in) {
;     ...
;         for (int dt = 0; dt < 4; ++dt)
; #pragma unroll
;             for (int ig = 0; ig < 4; ++ig) { const int d0 = 32 * dt + 8 * ig + 4 * hh;
;                 const u32x2 zz = *(const u32x2*)(P_proj + (poff + C_ZNSA + head * 128 + d0)); const u32x2 pv = totw[(dt * 4 + ig) * 64 + lane];
;                 const float o0 = st.acc[dt][4 * ig + 0] * inv + lo16(pv.x), o1 = st.acc[dt][4 * ig + 1] * inv + hi16(pv.x), o2 = st.acc[dt][4 * ig + 2] * inv + lo16(pv.y), o3 = st.acc[dt][4 * ig + 3] * inv + hi16(pv.y);
;                 u32x2 w; w.x = pk2(o0 * siluf_(lo16(zz.x)), o1 * siluf_(hi16(zz.x))); w.y = pk2(o2 * siluf_(lo16(zz.y)), o3 * siluf_(hi16(zz.y)));
;                 *(u32x2*)(P_onsa + (ooff + d0)) = w; }
	v_lshlrev_b32_e32 v16, 16, v2
	v_and_b32_e32 v17, 0xffff0000, v2
	v_lshlrev_b32_e32 v2, 16, v3
	v_and_b32_e32 v3, 0xffff0000, v3
	v_pk_fma_f32 v[16:17], v[32:33], v[6:7], v[16:17] op_sel_hi:[1,0,1]
	v_pk_fma_f32 v[2:3], v[34:35], v[6:7], v[2:3] op_sel_hi:[1,0,1]
	v_lshlrev_b32_e32 v20, 16, v14
	v_and_b32_e32 v21, 0xffff0000, v14
	v_lshlrev_b32_e32 v14, 16, v15
	v_and_b32_e32 v15, 0xffff0000, v15
	v_mul_f32_e32 v0, 0xbfb8aa3b, v20
	v_mul_f32_e32 v22, 0xbfb8aa3b, v21
	v_mul_f32_e32 v23, 0xbfb8aa3b, v14
	v_mul_f32_e32 v24, 0xbfb8aa3b, v15
	v_exp_f32_e32 v0, v0
	v_exp_f32_e32 v22, v22
	v_exp_f32_e32 v23, v23
	v_exp_f32_e32 v24, v24
	v_add_f32_e32 v0, 1.0, v0
	v_add_f32_e32 v25, 1.0, v22
	v_add_f32_e32 v26, 1.0, v23
	v_add_f32_e32 v27, 1.0, v24
	v_rcp_f32_e32 v22, v0
	v_rcp_f32_e32 v23, v25
	v_rcp_f32_e32 v24, v26
	v_rcp_f32_e32 v25, v27
	v_add_u32_e32 v0, v7, v28
	v_pk_mul_f32 v[20:21], v[22:23], v[20:21]
	v_lshl_add_u64 v[26:27], v[0:1], 1, s[30:31]
	v_pk_mul_f32 v[14:15], v[24:25], v[14:15]
	v_pk_mul_f32 v[16:17], v[16:17], v[20:21]
	v_pk_mul_f32 v[2:3], v[2:3], v[14:15]
	v_cvt_pk_bf16_f32 v14, v16, v17
	v_cvt_pk_bf16_f32 v15, v2, v3
	global_store_dwordx2 v[18:19], v[14:15], off
	v_mov_b64_e32 v[2:3], v[122:123]
	v_add_u32_e32 v0, v9, v28
	v_lshl_add_u64 v[16:17], v[0:1], 1, s[28:29]
	v_lshlrev_b32_e32 v14, 16, v4
	v_and_b32_e32 v15, 0xffff0000, v4
	v_lshlrev_b32_e32 v4, 16, v5
	v_and_b32_e32 v5, 0xffff0000, v5
	v_pk_fma_f32 v[14:15], v[36:37], v[6:7], v[14:15] op_sel_hi:[1,0,1]
	v_pk_fma_f32 v[4:5], v[38:39], v[6:7], v[4:5] op_sel_hi:[1,0,1]
	v_add_u32_e32 v26, 0x70, v8
	v_add_u32_e32 v8, 0x78, v8
	v_lshlrev_b32_e32 v18, 16, v2
	v_and_b32_e32 v19, 0xffff0000, v2
	v_lshlrev_b32_e32 v2, 16, v3
	v_and_b32_e32 v3, 0xffff0000, v3
	v_mul_f32_e32 v0, 0xbfb8aa3b, v18
	v_mul_f32_e32 v20, 0xbfb8aa3b, v19
	v_mul_f32_e32 v21, 0xbfb8aa3b, v2
	v_mul_f32_e32 v22, 0xbfb8aa3b, v3
	v_exp_f32_e32 v0, v0
	v_exp_f32_e32 v20, v20
	v_exp_f32_e32 v21, v21
	v_exp_f32_e32 v22, v22
	v_add_f32_e32 v0, 1.0, v0
	v_add_f32_e32 v23, 1.0, v20
	v_add_f32_e32 v24, 1.0, v21
	v_add_f32_e32 v25, 1.0, v22
	v_rcp_f32_e32 v20, v0
	v_rcp_f32_e32 v21, v23
	v_rcp_f32_e32 v22, v24
	v_rcp_f32_e32 v23, v25
	v_add_u32_e32 v0, v7, v26
	v_pk_mul_f32 v[18:19], v[20:21], v[18:19]
	v_lshl_add_u64 v[24:25], v[0:1], 1, s[30:31]
	v_pk_mul_f32 v[2:3], v[22:23], v[2:3]
	v_pk_mul_f32 v[14:15], v[14:15], v[18:19]
	v_pk_mul_f32 v[2:3], v[4:5], v[2:3]
	v_cvt_pk_bf16_f32 v4, v14, v15
	v_cvt_pk_bf16_f32 v5, v2, v3
	global_store_dwordx2 v[16:17], v[4:5], off
	v_mov_b64_e32 v[2:3], v[124:125]
	v_add_u32_e32 v0, v9, v26
	v_lshl_add_u64 v[14:15], v[0:1], 1, s[28:29]
	s_waitcnt lgkmcnt(0)
	v_lshlrev_b32_e32 v4, 16, v10
	v_and_b32_e32 v5, 0xffff0000, v10
	v_lshlrev_b32_e32 v10, 16, v11
	v_and_b32_e32 v11, 0xffff0000, v11
	v_pk_fma_f32 v[4:5], v[40:41], v[6:7], v[4:5] op_sel_hi:[1,0,1]
	v_pk_fma_f32 v[10:11], v[42:43], v[6:7], v[10:11] op_sel_hi:[1,0,1]
	v_lshlrev_b32_e32 v16, 16, v2
	v_and_b32_e32 v17, 0xffff0000, v2
	v_lshlrev_b32_e32 v2, 16, v3
	v_and_b32_e32 v3, 0xffff0000, v3
	v_mul_f32_e32 v0, 0xbfb8aa3b, v16
	v_mul_f32_e32 v18, 0xbfb8aa3b, v17
	v_mul_f32_e32 v19, 0xbfb8aa3b, v2
	v_mul_f32_e32 v20, 0xbfb8aa3b, v3
	v_exp_f32_e32 v0, v0
	v_exp_f32_e32 v18, v18
	v_exp_f32_e32 v19, v19
	v_exp_f32_e32 v20, v20
	v_add_f32_e32 v0, 1.0, v0
	v_add_f32_e32 v21, 1.0, v18
	v_add_f32_e32 v22, 1.0, v19
	v_add_f32_e32 v23, 1.0, v20
	v_rcp_f32_e32 v18, v0
	v_rcp_f32_e32 v19, v21
	v_rcp_f32_e32 v20, v22
	v_rcp_f32_e32 v21, v23
	v_add_u32_e32 v0, v7, v8
	v_pk_mul_f32 v[16:17], v[18:19], v[16:17]
	v_lshl_add_u64 v[22:23], v[0:1], 1, s[30:31]
	v_pk_mul_f32 v[2:3], v[20:21], v[2:3]
	v_pk_mul_f32 v[4:5], v[4:5], v[16:17]
	v_pk_mul_f32 v[2:3], v[10:11], v[2:3]
	v_cvt_pk_bf16_f32 v4, v4, v5
	v_cvt_pk_bf16_f32 v5, v2, v3
	global_store_dwordx2 v[14:15], v[4:5], off
	v_mov_b64_e32 v[2:3], v[126:127]
	v_lshlrev_b32_e32 v4, 16, v12
	v_and_b32_e32 v5, 0xffff0000, v12
	v_lshlrev_b32_e32 v10, 16, v13
	v_and_b32_e32 v11, 0xffff0000, v13
	v_pk_fma_f32 v[4:5], v[44:45], v[6:7], v[4:5] op_sel_hi:[1,0,1]
	v_pk_fma_f32 v[6:7], v[46:47], v[6:7], v[10:11] op_sel_hi:[1,0,1]
	v_lshlrev_b32_e32 v10, 16, v2
	v_and_b32_e32 v11, 0xffff0000, v2
	v_lshlrev_b32_e32 v2, 16, v3
	v_and_b32_e32 v3, 0xffff0000, v3
	v_mul_f32_e32 v0, 0xbfb8aa3b, v10
	v_mul_f32_e32 v12, 0xbfb8aa3b, v11
	v_mul_f32_e32 v13, 0xbfb8aa3b, v2
	v_mul_f32_e32 v14, 0xbfb8aa3b, v3
	v_exp_f32_e32 v0, v0
	v_exp_f32_e32 v12, v12
	v_exp_f32_e32 v13, v13
	v_exp_f32_e32 v14, v14
	v_add_f32_e32 v0, 1.0, v0
	v_add_f32_e32 v15, 1.0, v12
	v_add_f32_e32 v16, 1.0, v13
	v_add_f32_e32 v17, 1.0, v14
	v_rcp_f32_e32 v12, v0
	v_rcp_f32_e32 v13, v15
	v_rcp_f32_e32 v14, v16
	v_rcp_f32_e32 v15, v17
	v_add_u32_e32 v0, v9, v8
	v_pk_mul_f32 v[10:11], v[12:13], v[10:11]
	v_lshl_add_u64 v[8:9], v[0:1], 1, s[28:29]
	v_pk_mul_f32 v[2:3], v[14:15], v[2:3]
	v_pk_mul_f32 v[4:5], v[4:5], v[10:11]
	v_pk_mul_f32 v[2:3], v[6:7], v[2:3]
	v_cvt_pk_bf16_f32 v4, v4, v5
	v_cvt_pk_bf16_f32 v5, v2, v3
	global_store_dwordx2 v[8:9], v[4:5], off
	s_cbranch_scc0 .LBB0_562
